# v044 + gla_prep item-start wait counted: vmcnt(0) to vmcnt(9) so the previous item's 9 output stores stay in flight while the prefetched loads are consumed
# baseline (speedup 1.0000x reference)
.LBB0_2474:
	v_add_u32_e32 v2, v70, v78
	v_add_u32_e32 v98, v70, v79
	s_waitcnt vmcnt(9)
	ds_write_b128 v2, v[20:23]
	ds_write_b128 v2, v[24:27] offset:33792
	ds_write_b128 v98, v[28:31]
	ds_write_b128 v98, v[32:35] offset:33792
	ds_write_b128 v2, v[36:39] offset:16896
	ds_write_b128 v2, v[40:43] offset:50688
	v_add_u32_e32 v2, v70, v80
	ds_write_b128 v2, v[44:47]
	ds_write_b128 v2, v[48:51] offset:33792
	s_and_saveexec_b64 s[38:39], s[0:1]
	ds_write_b128 v93, v[52:55]
	s_or_b64 exec, exec, s[38:39]
	s_add_i32 s89, s89, s96
	s_cmpk_gt_i32 s89, 0x7ff
	s_cselect_b64 s[58:59], -1, 0
	s_and_b64 vcc, exec, s[58:59]
	s_waitcnt lgkmcnt(0)
	s_barrier
	s_cbranch_vccnz .LBB0_2480
	s_add_i32 s54, s87, s57
	s_andn2_b32 s54, s54, 63
	s_and_b32 s38, s90, 0x300
	v_or_b32_e32 v20, s54, v64
	v_or_b32_e32 v28, s54, v65
	v_or_b32_e32 v36, s54, v66
	v_or_b32_e32 v44, s54, v67
	v_or_b32_e32 v2, s38, v59
	v_ashrrev_i32_e32 v21, 31, v20
	v_ashrrev_i32_e32 v29, 31, v28
	v_ashrrev_i32_e32 v37, 31, v36
	v_ashrrev_i32_e32 v45, 31, v44
	v_lshlrev_b64 v[20:21], 11, v[20:21]
	v_lshlrev_b32_e32 v2, 1, v2
	v_lshlrev_b64 v[28:29], 11, v[28:29]
	v_lshlrev_b64 v[36:37], 11, v[36:37]
	v_lshlrev_b64 v[44:45], 11, v[44:45]
	v_or_b32_e32 v20, v20, v2
	v_or_b32_e32 v28, v28, v2
	v_or_b32_e32 v36, v36, v2
	v_or_b32_e32 v44, v44, v2
	v_lshl_add_u64 v[22:23], s[44:45], 0, v[20:21]
	v_lshl_add_u64 v[24:25], s[46:47], 0, v[20:21]
	v_lshl_add_u64 v[30:31], s[44:45], 0, v[28:29]
	v_lshl_add_u64 v[32:33], s[46:47], 0, v[28:29]
	v_lshl_add_u64 v[38:39], s[44:45], 0, v[36:37]
	v_lshl_add_u64 v[40:41], s[46:47], 0, v[36:37]
	v_lshl_add_u64 v[46:47], s[44:45], 0, v[44:45]
	v_lshl_add_u64 v[48:49], s[46:47], 0, v[44:45]
	global_load_dwordx4 v[20:23], v[22:23], off
	s_nop 0
	global_load_dwordx4 v[24:27], v[24:25], off
	s_nop 0
	global_load_dwordx4 v[28:31], v[30:31], off
	s_nop 0
	global_load_dwordx4 v[32:35], v[32:33], off
	s_nop 0
	global_load_dwordx4 v[36:39], v[38:39], off
	s_nop 0
	global_load_dwordx4 v[40:43], v[40:41], off
	s_nop 0
	global_load_dwordx4 v[44:47], v[46:47], off
	s_nop 0
	global_load_dwordx4 v[48:51], v[48:49], off
	s_and_saveexec_b64 s[38:39], s[0:1]
	s_cbranch_execz .LBB0_2479
	v_or_b32_e32 v52, s54, v68
	v_ashrrev_i32_e32 v53, 31, v52
	v_readlane_b32 s4, v254, 24
	v_lshlrev_b64 v[52:53], 7, v[52:53]
	v_readlane_b32 s5, v254, 25
	s_and_b32 s54, s92, 16
	s_lshl_b32 s54, s54, 2
	v_lshl_add_u64 v[52:53], s[4:5], 0, v[52:53]
	v_lshl_add_u64 v[52:53], v[52:53], 0, s[54:55]
	v_lshl_add_u64 v[52:53], v[56:57], 2, v[52:53]
	global_load_dwordx4 v[52:55], v[52:53], off
